# speedup vs baseline: 1.0054x; 1.0031x over previous
.LBB0_511:
	s_or_b64 exec, exec, s[8:9]
	v_add_u32_e32 v115, 0xfffff000, v158
	s_movk_i32 s8, 0xfff
	v_ashrrev_i32_e32 v115, 10, v115
	v_cmp_lt_i32_e32 vcc, s8, v158
	s_nop 1
	v_cndmask_b32_e32 v141, 8, v115, vcc
	v_cmp_ne_u32_e32 vcc, v141, v113
	s_and_saveexec_b64 s[8:9], vcc
	s_cbranch_execz .LBB0_502
	v_readlane_b32 s10, v255, 8
	v_mov_b64_e32 v[32:33], s[84:85]
	v_lshlrev_b32_e32 v196, 2, v96
	v_add_u32_e32 v34, s10, v141
	v_mad_i64_i32 v[92:93], s[10:11], v34, s3, v[32:33]
	s_mov_b64 s[10:11], 0x2000
	s_nop 0
	v_lshl_add_u64 v[94:95], v[92:93], 0, s[10:11]
	v_lshl_add_u64 v[40:41], v[94:95], 0, v[196:197]
	v_lshl_add_u64 v[76:77], v[92:93], 0, v[196:197]
	v_mov_b32_e32 v113, v197
	v_lshl_add_u64 v[44:45], v[94:95], 0, v[112:113]
	v_mov_b32_e32 v115, v197
	v_lshl_add_u64 v[48:49], v[94:95], 0, v[114:115]
	v_mov_b32_e32 v117, v197
	v_lshl_add_u64 v[78:79], v[94:95], 0, v[116:117]
	v_mov_b32_e32 v119, v197
	v_lshl_add_u64 v[88:89], v[94:95], 0, v[118:119]
	v_mov_b32_e32 v121, v197
	v_lshl_add_u64 v[148:149], v[94:95], 0, v[120:121]
	v_mov_b32_e32 v123, v197
	v_lshl_add_u64 v[156:157], v[94:95], 0, v[122:123]
	v_mov_b32_e32 v125, v197
	v_lshl_add_u64 v[160:161], v[94:95], 0, v[124:125]
	v_mov_b32_e32 v113, v141
	global_load_dwordx4 v[32:35], v[76:77], off
	global_load_dwordx4 v[126:129], v[98:99], off
	global_load_dwordx4 v[204:207], v[40:41], off
	global_load_dwordx4 v[36:39], v[76:77], off offset:1024
	global_load_dwordx4 v[130:133], v[98:99], off offset:1024
	global_load_dwordx4 v[208:211], v[44:45], off
	global_load_dwordx4 v[40:43], v[76:77], off offset:2048
	global_load_dwordx4 v[134:137], v[98:99], off offset:2048
	global_load_dwordx4 v[212:215], v[48:49], off
	global_load_dwordx4 v[44:47], v[76:77], off offset:3072
	global_load_dwordx4 v[240:243], v[98:99], off offset:3072
	global_load_dwordx4 v[216:219], v[78:79], off
	v_lshl_add_u64 v[48:49], v[92:93], 0, v[118:119]
	global_load_dwordx4 v[48:51], v[48:49], off
	global_load_dwordx4 v[144:147], v[100:101], off
	global_load_dwordx4 v[220:223], v[88:89], off
	v_lshl_add_u64 v[248:249], v[92:93], 0, v[120:121]
	global_load_dwordx4 v[76:79], v[248:249], off
	global_load_dwordx4 v[228:231], v[148:149], off
	s_nop 0
	global_load_dwordx4 v[148:151], v[102:103], off
	v_lshl_add_u64 v[250:251], v[92:93], 0, v[122:123]
	global_load_dwordx4 v[88:91], v[250:251], off
	global_load_dwordx4 v[152:155], v[104:105], off
	global_load_dwordx4 v[232:235], v[156:157], off
	global_load_dwordx4 v[236:239], v[160:161], off
	global_load_dwordx4 v[244:247], v[106:107], off
	v_lshl_add_u64 v[92:93], v[92:93], 0, v[124:125]
	global_load_dwordx4 v[92:95], v[92:93], off
	s_waitcnt vmcnt(0)
	v_pk_add_f32 v[204:205], v[204:205], 1.0 op_sel_hi:[1,0]
	v_pk_add_f32 v[206:207], v[206:207], 1.0 op_sel_hi:[1,0]
	s_nop 0
	v_pk_mul_f32 v[126:127], v[126:127], v[204:205]
	v_pk_mul_f32 v[128:129], v[128:129], v[206:207]
	v_pk_add_f32 v[208:209], v[208:209], 1.0 op_sel_hi:[1,0]
	v_pk_add_f32 v[210:211], v[210:211], 1.0 op_sel_hi:[1,0]
	s_nop 0
	v_pk_mul_f32 v[130:131], v[130:131], v[208:209]
	v_pk_mul_f32 v[132:133], v[132:133], v[210:211]
	v_pk_add_f32 v[212:213], v[212:213], 1.0 op_sel_hi:[1,0]
	v_pk_add_f32 v[214:215], v[214:215], 1.0 op_sel_hi:[1,0]
	s_nop 0
	v_pk_mul_f32 v[134:135], v[134:135], v[212:213]
	v_pk_mul_f32 v[136:137], v[136:137], v[214:215]
	v_pk_add_f32 v[216:217], v[216:217], 1.0 op_sel_hi:[1,0]
	v_pk_add_f32 v[218:219], v[218:219], 1.0 op_sel_hi:[1,0]
	s_nop 0
	v_pk_mul_f32 v[138:139], v[240:241], v[216:217]
	v_pk_mul_f32 v[142:143], v[242:243], v[218:219]
	v_pk_add_f32 v[220:221], v[220:221], 1.0 op_sel_hi:[1,0]
	v_pk_add_f32 v[222:223], v[222:223], 1.0 op_sel_hi:[1,0]
	s_nop 0
	v_pk_mul_f32 v[144:145], v[144:145], v[220:221]
	v_pk_mul_f32 v[146:147], v[146:147], v[222:223]
	v_pk_add_f32 v[228:229], v[228:229], 1.0 op_sel_hi:[1,0]
	v_pk_add_f32 v[230:231], v[230:231], 1.0 op_sel_hi:[1,0]
	s_nop 0
	v_pk_mul_f32 v[148:149], v[148:149], v[228:229]
	v_pk_mul_f32 v[150:151], v[150:151], v[230:231]
	v_pk_add_f32 v[232:233], v[232:233], 1.0 op_sel_hi:[1,0]
	v_pk_add_f32 v[234:235], v[234:235], 1.0 op_sel_hi:[1,0]
	s_nop 0
	v_pk_mul_f32 v[152:153], v[152:153], v[232:233]
	v_pk_mul_f32 v[154:155], v[154:155], v[234:235]
	v_pk_add_f32 v[236:237], v[236:237], 1.0 op_sel_hi:[1,0]
	v_pk_add_f32 v[238:239], v[238:239], 1.0 op_sel_hi:[1,0]
	s_nop 0
	v_pk_mul_f32 v[156:157], v[244:245], v[236:237]
	v_pk_mul_f32 v[160:161], v[246:247], v[238:239]
	s_branch .LBB0_502
